# adds: prologue item search by direct computation, W_q row loads batched, input-row sum-of-squares loop pipelined one trip ahead
# baseline (speedup 1.0000x reference)
.LBB0_727:
	s_mov_b32 s85, s92
	s_cmp_lt_u32 s85, 0x5800
	s_cbranch_scc0 .Lit_hi
	s_lshr_b32 s8, s85, 9
	s_mul_i32 s9, s8, 0x1746
	s_lshr_b32 s9, s9, 16
	s_mul_i32 s10, s9, 0x1600
	s_sub_i32 s85, s85, s10
	s_mul_i32 s93, s9, 6
	s_add_i32 s93, s93, 1
	s_cmp_lt_u32 s85, 0x200
	s_cbranch_scc1 .Lit_done
	s_sub_i32 s85, s85, 0x200
	s_add_i32 s93, s93, 1
	s_cmp_lt_u32 s85, 0x200
	s_cbranch_scc1 .Lit_done
	s_sub_i32 s85, s85, 0x200
	s_add_i32 s93, s93, 1
	s_cmp_lt_u32 s85, 0x200
	s_cbranch_scc1 .Lit_done
	s_sub_i32 s85, s85, 0x200
	s_add_i32 s93, s93, 1
	s_cmp_lt_u32 s85, 0x800
	s_cbranch_scc1 .Lit_done
	s_sub_i32 s85, s85, 0x800
	s_add_i32 s93, s93, 1
	s_branch .Lit_done
.Lit_hi:
	s_sub_i32 s85, s85, 0x5800
	s_mov_b32 s93, 24
	s_cmp_lt_u32 s85, 0x400
	s_cbranch_scc1 .Lit_done
	s_sub_i32 s85, s85, 0x400
	s_mov_b32 s93, 25
	s_cmp_lt_u32 s85, 0x200
	s_cbranch_scc1 .Lit_done
	s_sub_i32 s85, s85, 0x200
	s_mov_b32 s93, 26
	s_cmp_lt_u32 s85, 0x400
	s_cbranch_scc1 .Lit_done
	s_sub_i32 s85, s85, 0x400
	s_mov_b32 s93, 27
	s_cmp_lt_u32 s85, 0x200
	s_cbranch_scc1 .Lit_done
	s_sub_i32 s85, s85, 0x200
	s_lshr_b32 s8, s85, 5
	s_add_i32 s93, s8, 28
	s_and_b32 s85, s85, 31
.Lit_done:
.LBB0_752:
	s_cmp_gt_u32 s93, 23
	s_mov_b64 s[12:13], -1
	s_cbranch_scc0 .LBB0_762
	s_cmp_gt_u32 s93, 27
	s_mov_b64 s[8:9], -1
	s_cbranch_scc0 .LBB0_755
	s_sub_i32 s38, s93, 28
	s_lshr_b32 s12, s38, 2
	s_lshl_b64 s[8:9], s[38:39], 18
	s_waitcnt lgkmcnt(0)
	s_add_u32 s40, s72, s8
	s_addc_u32 s41, s73, s9
	s_lshl_b64 s[8:9], s[38:39], 17
	s_add_u32 s42, s7, s8
	s_addc_u32 s43, s25, s9
	s_lshl_b32 s38, s12, 11
	s_lshl_b64 s[8:9], s[38:39], 2
	s_add_u32 s8, s48, s8
	s_addc_u32 s9, s49, s9
	s_lshl_b32 s10, s93, 10
	s_and_b32 s13, s10, 0xc00
	s_add_u32 s10, s8, s13
	s_addc_u32 s11, s9, 0
	s_lshl_b32 s38, s12, 10
	s_lshl_b64 s[8:9], s[38:39], 2
	s_add_u32 s8, s74, s8
	s_addc_u32 s9, s75, s9
	s_add_u32 s14, s8, s13
	s_addc_u32 s15, s9, 0
	s_mov_b64 s[8:9], 0

.LBB0_806:
	global_load_dword v10, v141, s[8:9]
	global_load_dwordx4 v[6:9], v[4:5], off offset:-3072
	global_load_dwordx4 v[52:55], v[4:5], off offset:-2048
	global_load_dwordx4 v[56:59], v[4:5], off offset:-1024
	global_load_dwordx4 v[60:63], v[4:5], off
	s_add_i32 s4, s4, s80
	s_add_u32 s8, s8, s30
	s_addc_u32 s9, s9, s31
	s_cmpk_gt_i32 s4, 0xfff
	s_waitcnt vmcnt(0)
	v_pk_mul_f32 v[6:7], v[6:7], v[10:11] op_sel_hi:[1,0]
	v_pk_mul_f32 v[8:9], v[8:9], v[10:11] op_sel_hi:[1,0]
	v_cvt_pk_bf16_f32 v6, v6, v7
	s_nop 0
	v_cvt_pk_bf16_f32 v7, v8, v9
	global_store_dwordx2 v[2:3], v[6:7], off
	v_mov_b32_e32 v6, v52
	v_mov_b32_e32 v7, v53
	v_mov_b32_e32 v8, v54
	v_mov_b32_e32 v9, v55
	s_nop 0
	v_pk_mul_f32 v[6:7], v[10:11], v[6:7] op_sel_hi:[0,1]
	v_pk_mul_f32 v[8:9], v[10:11], v[8:9] op_sel_hi:[0,1]
	v_cvt_pk_bf16_f32 v6, v6, v7
	v_cvt_pk_bf16_f32 v7, v8, v9
	global_store_dwordx2 v[2:3], v[6:7], off offset:512
	v_mov_b32_e32 v6, v56
	v_mov_b32_e32 v7, v57
	v_mov_b32_e32 v8, v58
	v_mov_b32_e32 v9, v59
	s_nop 0
	v_pk_mul_f32 v[6:7], v[10:11], v[6:7] op_sel_hi:[0,1]
	v_pk_mul_f32 v[8:9], v[10:11], v[8:9] op_sel_hi:[0,1]
	v_cvt_pk_bf16_f32 v6, v6, v7
	v_cvt_pk_bf16_f32 v7, v8, v9
	global_store_dwordx2 v[2:3], v[6:7], off offset:1024
	v_mov_b32_e32 v6, v60
	v_mov_b32_e32 v7, v61
	v_mov_b32_e32 v8, v62
	v_mov_b32_e32 v9, v63
	v_lshl_add_u64 v[4:5], v[4:5], 0, s[10:11]
	s_nop 0
	v_pk_mul_f32 v[6:7], v[10:11], v[6:7] op_sel_hi:[0,1]
	v_pk_mul_f32 v[8:9], v[10:11], v[8:9] op_sel_hi:[0,1]
	v_cvt_pk_bf16_f32 v6, v6, v7
	v_cvt_pk_bf16_f32 v7, v8, v9
	global_store_dwordx2 v[2:3], v[6:7], off offset:1536
	v_lshl_add_u64 v[2:3], v[2:3], 0, s[2:3]
	s_cbranch_scc0 .LBB0_806
	s_add_u32 s4, s0, 0x2d800000
	v_lshlrev_b32_e32 v2, 2, v42
	s_addc_u32 s5, s1, 0
	v_lshl_add_u64 v[0:1], s[46:47], 0, v[0:1]
	s_mov_b64 s[0:1], 0xc00
	v_xor_b32_e32 v20, 4, v2
	v_xor_b32_e32 v21, 8, v2
	v_xor_b32_e32 v22, 16, v2
	v_xor_b32_e32 v23, 32, v2
	v_xor_b32_e32 v24, 64, v2
	v_xor_b32_e32 v25, 0x80, v2
	v_cmp_eq_u32_e64 s[40:41], 0, v42
	v_lshl_add_u64 v[18:19], v[0:1], 0, s[0:1]
	s_mov_b32 s7, s6
	s_branch .LBB0_809

.LBB0_811:
	s_cmp_gt_i32 s6, 0xffff
	s_cbranch_scc1 .LBB0_817
	v_lshlrev_b32_e32 v140, 4, v42
	v_readlane_b32 s0, v255, 29
	v_lshl_add_u64 v[0:1], s[44:45], 0, v[140:141]
	v_lshlrev_b32_e32 v140, 2, v42
	v_readlane_b32 s1, v255, 30
	v_xor_b32_e32 v4, 4, v140
	v_xor_b32_e32 v5, 8, v140
	v_xor_b32_e32 v6, 16, v140
	v_xor_b32_e32 v7, 32, v140
	v_xor_b32_e32 v8, 64, v140
	v_xor_b32_e32 v9, 0x80, v140
	v_cmp_gt_u32_e32 vcc, 16, v42
	v_cmp_eq_u32_e64 s[40:41], 0, v42
	v_lshl_add_u64 v[2:3], s[0:1], 0, v[140:141]
	s_mov_b32 s100, s6
	s_mov_b32 s101, 0
	s_add_i32 s8, s100, s80
	s_cmp_lt_i32 s8, 0x10000
	s_cselect_b32 s8, s8, s100
	s_lshl_b64 s[100:101], s[100:101], 12
	v_lshl_add_u64 v[84:85], v[0:1], 0, s[100:101]
	global_load_dwordx4 v[52:55], v[84:85], off
	global_load_dwordx4 v[56:59], v[84:85], off offset:1024
	global_load_dwordx4 v[60:63], v[84:85], off offset:2048
	global_load_dwordx4 v[64:67], v[84:85], off offset:3072
	s_mov_b32 s9, 0
	s_lshl_b64 s[8:9], s[8:9], 12
	v_lshl_add_u64 v[84:85], v[0:1], 0, s[8:9]
	global_load_dwordx4 v[68:71], v[84:85], off
	global_load_dwordx4 v[72:75], v[84:85], off offset:1024
	global_load_dwordx4 v[76:79], v[84:85], off offset:2048
	global_load_dwordx4 v[80:83], v[84:85], off offset:3072
	s_branch .LBB0_814

.LBB0_814:
	s_add_i32 s4, s6, s80
	s_cmp_lt_i32 s4, 0x10000
	s_cselect_b32 s0, s4, s6
	s_ashr_i32 s7, s6, 31
	s_ashr_i32 s1, s0, 31
	s_waitcnt vmcnt(0) lgkmcnt(0)
	v_mov_b32_e32 v10, v52
	v_mov_b32_e32 v11, v53
	v_mov_b32_e32 v12, v54
	v_mov_b32_e32 v13, v55
	v_mov_b32_e32 v14, v56
	v_mov_b32_e32 v15, v57
	v_mov_b32_e32 v16, v58
	v_mov_b32_e32 v17, v59
	v_mov_b32_e32 v18, v60
	v_mov_b32_e32 v19, v61
	v_mov_b32_e32 v20, v62
	v_mov_b32_e32 v21, v63
	v_mov_b32_e32 v22, v64
	v_mov_b32_e32 v23, v65
	v_mov_b32_e32 v24, v66
	v_mov_b32_e32 v25, v67
	v_mov_b32_e32 v26, v68
	v_mov_b32_e32 v27, v69
	v_mov_b32_e32 v28, v70
	v_mov_b32_e32 v29, v71
	v_mov_b32_e32 v30, v72
	v_mov_b32_e32 v31, v73
	v_mov_b32_e32 v32, v74
	v_mov_b32_e32 v33, v75
	v_mov_b32_e32 v34, v76
	v_mov_b32_e32 v35, v77
	v_mov_b32_e32 v36, v78
	v_mov_b32_e32 v37, v79
	v_mov_b32_e32 v38, v80
	v_mov_b32_e32 v39, v81
	v_mov_b32_e32 v40, v82
	v_mov_b32_e32 v41, v83
	s_add_i32 s100, s4, s80
	s_cmp_gt_i32 s100, 0xffff
	s_cbranch_scc1 .Lxs_nopf
	s_mov_b32 s101, 0
	s_add_i32 s8, s100, s80
	s_cmp_lt_i32 s8, 0x10000
	s_cselect_b32 s8, s8, s100
	s_lshl_b64 s[100:101], s[100:101], 12
	v_lshl_add_u64 v[84:85], v[0:1], 0, s[100:101]
	global_load_dwordx4 v[52:55], v[84:85], off
	global_load_dwordx4 v[56:59], v[84:85], off offset:1024
	global_load_dwordx4 v[60:63], v[84:85], off offset:2048
	global_load_dwordx4 v[64:67], v[84:85], off offset:3072
	s_mov_b32 s9, 0
	s_lshl_b64 s[8:9], s[8:9], 12
	v_lshl_add_u64 v[84:85], v[0:1], 0, s[8:9]
	global_load_dwordx4 v[68:71], v[84:85], off
	global_load_dwordx4 v[72:75], v[84:85], off offset:1024
	global_load_dwordx4 v[76:79], v[84:85], off offset:2048
	global_load_dwordx4 v[80:83], v[84:85], off offset:3072
.Lxs_nopf:
	v_mul_f32_e32 v11, v11, v11
	v_mul_f32_e32 v13, v13, v13
	v_mul_f32_e32 v15, v15, v15
	v_mul_f32_e32 v17, v17, v17
	v_mul_f32_e32 v19, v19, v19
	v_mul_f32_e32 v21, v21, v21
	v_fmac_f32_e32 v11, v10, v10
	v_fmac_f32_e32 v13, v12, v12
	v_mul_f32_e32 v10, v27, v27
	v_mul_f32_e32 v12, v29, v29
	v_fmac_f32_e32 v15, v14, v14
	v_fmac_f32_e32 v17, v16, v16
	v_mul_f32_e32 v14, v31, v31
	v_mul_f32_e32 v16, v33, v33
	v_mul_f32_e32 v23, v23, v23
	v_mul_f32_e32 v25, v25, v25
	v_fmac_f32_e32 v19, v18, v18
	v_fmac_f32_e32 v21, v20, v20
	v_mul_f32_e32 v18, v35, v35
	v_mul_f32_e32 v20, v37, v37
	v_fmac_f32_e32 v10, v26, v26
	v_fmac_f32_e32 v12, v28, v28
	v_fmac_f32_e32 v14, v30, v30
	v_fmac_f32_e32 v16, v32, v32
	v_fmac_f32_e32 v23, v22, v22
	v_fmac_f32_e32 v25, v24, v24
	v_mul_f32_e32 v22, v39, v39
	v_mul_f32_e32 v24, v41, v41
	v_add_f32_e32 v11, v11, v13
	v_add_f32_e32 v13, v15, v17
	v_fmac_f32_e32 v18, v34, v34
	v_fmac_f32_e32 v20, v36, v36
	v_add_f32_e32 v10, v10, v12
	v_add_f32_e32 v12, v14, v16
	v_add_f32_e32 v15, v19, v21
	v_fmac_f32_e32 v22, v38, v38
	v_fmac_f32_e32 v24, v40, v40
	v_add_f32_e32 v11, v11, v13
	v_add_f32_e32 v13, v18, v20
	v_add_f32_e32 v10, v10, v12
	v_add_f32_e32 v17, v23, v25
	v_add_f32_e32 v14, v22, v24
	v_add_f32_e32 v11, v11, v15
	v_add_f32_e32 v10, v10, v13
	v_add_f32_e32 v11, v11, v17
	v_add_f32_e32 v10, v10, v14
	ds_bpermute_b32 v12, v4, v11
	ds_bpermute_b32 v13, v4, v10
	s_waitcnt lgkmcnt(1)
	v_add_f32_e32 v11, v11, v12
	s_waitcnt lgkmcnt(0)
	v_add_f32_e32 v10, v10, v13
	ds_bpermute_b32 v12, v5, v11
	ds_bpermute_b32 v13, v5, v10
	s_waitcnt lgkmcnt(1)
	v_add_f32_e32 v11, v11, v12
	s_waitcnt lgkmcnt(0)
	v_add_f32_e32 v10, v10, v13
	ds_bpermute_b32 v12, v6, v11
	ds_bpermute_b32 v13, v6, v10
	s_waitcnt lgkmcnt(1)
	v_add_f32_e32 v11, v11, v12
	s_waitcnt lgkmcnt(0)
	v_add_f32_e32 v10, v10, v13
	ds_bpermute_b32 v12, v7, v11
	ds_bpermute_b32 v13, v7, v10
	s_waitcnt lgkmcnt(1)
	v_add_f32_e32 v11, v11, v12
	s_waitcnt lgkmcnt(0)
	v_add_f32_e32 v10, v10, v13
	ds_bpermute_b32 v12, v8, v11
	ds_bpermute_b32 v14, v8, v10
	s_waitcnt lgkmcnt(1)
	v_add_f32_e32 v12, v11, v12
	s_waitcnt lgkmcnt(0)
	v_add_f32_e32 v10, v10, v14
	ds_bpermute_b32 v13, v9, v12
	ds_bpermute_b32 v11, v9, v10
	s_and_saveexec_b64 s[8:9], vcc
	s_cbranch_execz .LBB0_813
	s_waitcnt lgkmcnt(1)
	v_add_f32_e32 v12, v12, v13
	s_lshl_b64 s[10:11], s[6:7], 6
	v_cndmask_b32_e64 v14, 0, v12, s[40:41]
	v_lshl_add_u64 v[12:13], v[2:3], 0, s[10:11]
	s_cmp_eq_u32 s6, s0
	global_store_dword v[12:13], v14, off
	s_cbranch_scc1 .LBB0_813
	s_waitcnt lgkmcnt(0)
	v_add_f32_e32 v10, v10, v11
	s_lshl_b64 s[0:1], s[0:1], 6
	v_cndmask_b32_e64 v12, 0, v10, s[40:41]
	v_lshl_add_u64 v[10:11], v[2:3], 0, s[0:1]
	global_store_dword v[10:11], v12, off
	s_branch .LBB0_813
